# NSA selected branch: row-sum of the 16 exp values per head via packed pairwise add tree instead of 16-deep serial add chain
# speedup vs baseline: 1.0065x; 1.0065x over previous
; DI void nsa_item(const Params& p, int bk, int qb, char* smem, float Mb) {
;     ...
;         while (j <= cur) {
;             const int jn = next_valid(j + 1, mn);
;             gload(jn <= cur ? jn : j);
;             const unsigned sub = (unsigned)(m >> (wave * 16)) & 0xffffu;
;             if (sub) {
;                 const char* kb_ = tb + bsel * 18432 + fr * 144 + fq * 16;
;                 bf16x8 kf[4][2], vf[4][2];
; #pragma unroll
;                 for (int k4 = 0; k4 < 4; ++k4) {
;                     kf[k4][0] = *(const bf16x8*)(kb_ + k4 * 16 * 144); kf[k4][1] = *(const bf16x8*)(kb_ + k4 * 16 * 144 + 64);
;                     vf[k4][0] = *(const bf16x8*)(kb_ + 9216 + k4 * 16 * 144); vf[k4][1] = *(const bf16x8*)(kb_ + 9216 + k4 * 16 * 144 + 64);
;                 }
;                 const bool mine = (sub >> fr) & 1u;
;                 const float Ml = mine ? Mb : 3.0e38f;
;                 const bool diag = (j == cur);
; #pragma unroll
;                 for (int g = 0; g < 3; ++g) {
;                     f32x4 st[4];
;                     st_from(kf, qf[g], st, -Ml);
;                     if (diag) {
; #pragma unroll
;                         for (int k4 = 0; k4 < 4; ++k4)
; #pragma unroll
;                             for (int ii = 0; ii < 4; ++ii) {
;                                 const float pv = (j * 64 + k4 * 16 + fq * 4 + ii <= tq) ? __builtin_amdgcn_exp2f(st[k4][ii]) : 0.f;
;                                 st[k4][ii] = pv; ls[g] += pv;
;                             }
;                     } else {
; #pragma unroll
;                         for (int k4 = 0; k4 < 4; ++k4)
; #pragma unroll
;                             for (int ii = 0; ii < 4; ++ii) { const float pv = __builtin_amdgcn_exp2f(st[k4][ii]); st[k4][ii] = pv; ls[g] += pv; }
;                     }
;                     pv_from(vf, st, o[g]);
;                 }
.LBB0_546:
	s_or_b64 exec, exec, s[8:9]
	v_cmp_gt_i32_e64 s[4:5], v242, v238
	v_mov_b32_e32 v207, v189
	v_mov_b32_e32 v205, v189
	v_cndmask_b32_e64 v72, v242, v245, s[4:5]
	v_ashrrev_i32_e32 v73, 31, v72
	v_lshlrev_b64 v[80:81], 13, v[72:73]
	v_lshl_add_u64 v[72:73], s[50:51], 0, v[80:81]
	v_lshl_add_u64 v[80:81], s[36:37], 0, v[80:81]
	v_lshl_add_u64 v[74:75], v[72:73], 0, v[188:189]
	v_lshl_add_u64 v[72:73], v[72:73], 0, v[206:207]
	v_lshl_add_u64 v[82:83], v[80:81], 0, v[188:189]
	v_lshl_add_u64 v[80:81], v[80:81], 0, v[206:207]
	v_lshl_add_u64 v[74:75], v[74:75], 0, v[204:205]
	v_lshl_add_u64 v[76:77], v[72:73], 0, v[204:205]
	v_lshl_add_u64 v[82:83], v[82:83], 0, v[204:205]
	v_lshl_add_u64 v[84:85], v[80:81], 0, v[204:205]
	global_load_dwordx4 v[72:75], v[74:75], off
	s_nop 0
	global_load_dwordx4 v[76:79], v[76:77], off
	s_nop 0
	global_load_dwordx4 v[80:83], v[82:83], off
	s_nop 0
	global_load_dwordx4 v[84:87], v[84:85], off
	v_lshrrev_b64 v[88:89], s93, v[88:89]
	v_cmp_ne_u32_sdwa s[6:7], v88, v189 src0_sel:WORD_0 src1_sel:DWORD
	s_and_saveexec_b64 s[12:13], s[6:7]
	s_cbranch_execz .LBB0_534
	s_mul_i32 s6, s22, 0x4800
	v_add_u32_e32 v116, s6, v239
	ds_read_b128 v[120:123], v116
	ds_read_b128 v[128:131], v116 offset:64
	ds_read_b128 v[132:135], v116 offset:2304
	ds_read_b128 v[136:139], v116 offset:2368
	ds_read_b128 v[144:147], v116 offset:4608
	v_and_b32_e32 v88, v240, v88
	v_cmp_ne_u32_e64 s[6:7], 0, v88
	ds_read_b128 v[148:151], v116 offset:4672
	ds_read_b128 v[152:155], v116 offset:6912
	v_cndmask_b32_e64 v124, v229, v235, s[6:7]
	v_mov_b32_e32 v125, v124
	v_mov_b32_e32 v126, v124
	v_mov_b32_e32 v127, v124
	v_cmp_ne_u32_e64 s[6:7], v245, v238
	s_waitcnt lgkmcnt(4)
	v_mfma_f32_16x16x32_bf16 v[92:95], v[132:135], v[0:3], v[124:127]
	v_mfma_f32_16x16x32_bf16 v[88:91], v[120:123], v[0:3], v[124:127]
	s_waitcnt lgkmcnt(3)
	v_mfma_f32_16x16x32_bf16 v[176:179], v[136:139], v[4:7], v[92:95]
	s_waitcnt lgkmcnt(2)
	v_mfma_f32_16x16x32_bf16 v[92:95], v[144:147], v[0:3], v[124:127]
	v_mfma_f32_16x16x32_bf16 v[184:187], v[128:131], v[4:7], v[88:91]
	ds_read_b128 v[108:111], v116 offset:9216
	s_nop 1
	ds_read_b128 v[88:91], v116 offset:9280
	ds_read_b128 v[140:143], v116 offset:6976
	s_waitcnt lgkmcnt(3)
	v_mfma_f32_16x16x32_bf16 v[156:159], v[152:155], v[0:3], v[124:127]
	v_mfma_f32_16x16x32_bf16 v[168:171], v[148:151], v[4:7], v[92:95]
	s_nop 2
	ds_read_b128 v[92:95], v116 offset:11520
	ds_read_b128 v[96:99], v116 offset:11584
	ds_read_b128 v[100:103], v116 offset:13824
	ds_read_b128 v[104:107], v116 offset:13888
	ds_read_b128 v[112:115], v116 offset:16128
	ds_read_b128 v[116:119], v116 offset:16192
	s_waitcnt lgkmcnt(6)
	v_mfma_f32_16x16x32_bf16 v[160:163], v[140:143], v[4:7], v[156:159]
	s_and_saveexec_b64 s[8:9], s[6:7]
	s_xor_b64 s[8:9], exec, s[8:9]
	s_cbranch_execz .LBB0_549
	v_exp_f32_e32 v156, v184
	v_exp_f32_e32 v157, v185
	v_exp_f32_e32 v158, v186
	v_exp_f32_e32 v159, v187
	v_exp_f32_e32 v164, v176
	v_exp_f32_e32 v165, v177
	v_exp_f32_e32 v166, v178
	v_exp_f32_e32 v167, v179
	v_exp_f32_e32 v172, v168
	v_exp_f32_e32 v173, v169
	v_exp_f32_e32 v174, v170
	v_exp_f32_e32 v175, v171
	v_exp_f32_e32 v180, v160
	v_exp_f32_e32 v181, v161
	v_exp_f32_e32 v182, v162
	v_exp_f32_e32 v183, v163
	v_pk_add_f32 v[184:185], v[156:157], v[158:159]
	v_pk_add_f32 v[186:187], v[164:165], v[166:167]
	v_pk_add_f32 v[176:177], v[172:173], v[174:175]
	v_pk_add_f32 v[178:179], v[180:181], v[182:183]
	v_pk_add_f32 v[184:185], v[184:185], v[186:187]
	v_pk_add_f32 v[176:177], v[176:177], v[178:179]
	v_pk_add_f32 v[184:185], v[184:185], v[176:177]
	v_add_f32_e32 v244, v244, v184
	v_add_f32_e32 v244, v244, v185

; DI void nsa_item(const Params& p, int bk, int qb, char* smem, float Mb) {
;     ...
; #pragma unroll
;                 for (int g = 0; g < 3; ++g) {
;                     f32x4 st[4];
;                     st_from(kf, qf[g], st, -Ml);
;                     if (diag) {
; #pragma unroll
;                         for (int k4 = 0; k4 < 4; ++k4)
; #pragma unroll
;                             for (int ii = 0; ii < 4; ++ii) {
;                                 const float pv = (j * 64 + k4 * 16 + fq * 4 + ii <= tq) ? __builtin_amdgcn_exp2f(st[k4][ii]) : 0.f;
;                                 st[k4][ii] = pv; ls[g] += pv;
;                             }
;                     } else {
; #pragma unroll
;                         for (int k4 = 0; k4 < 4; ++k4)
; #pragma unroll
;                             for (int ii = 0; ii < 4; ++ii) { const float pv = __builtin_amdgcn_exp2f(st[k4][ii]); st[k4][ii] = pv; ls[g] += pv; }
;                     }
;                     pv_from(vf, st, o[g]);
;                 }
.LBB0_551:
	s_or_b64 exec, exec, s[14:15]
	v_cvt_pk_bf16_f32 v156, v156, v157
	v_cvt_pk_bf16_f32 v157, v158, v159
	v_cvt_pk_bf16_f32 v158, v164, v165
	v_cvt_pk_bf16_f32 v159, v166, v167
	v_cvt_pk_bf16_f32 v160, v172, v173
	v_cvt_pk_bf16_f32 v161, v174, v175
	v_mfma_f32_16x16x32_bf16 v[68:71], v[108:111], v[156:159], v[68:71]
	v_cvt_pk_bf16_f32 v162, v180, v181
	v_cvt_pk_bf16_f32 v163, v182, v183
	s_waitcnt lgkmcnt(5)
	v_mfma_f32_16x16x32_bf16 v[64:67], v[92:95], v[156:159], v[64:67]
	s_waitcnt lgkmcnt(3)
	v_mfma_f32_16x16x32_bf16 v[60:63], v[100:103], v[156:159], v[60:63]
	s_waitcnt lgkmcnt(1)
	v_mfma_f32_16x16x32_bf16 v[56:59], v[112:115], v[156:159], v[56:59]
	v_mfma_f32_16x16x32_bf16 v[156:159], v[120:123], v[8:11], v[124:127]
	v_mfma_f32_16x16x32_bf16 v[184:187], v[128:131], v[12:15], v[156:159]
	v_mfma_f32_16x16x32_bf16 v[156:159], v[132:135], v[8:11], v[124:127]
	v_mfma_f32_16x16x32_bf16 v[176:179], v[136:139], v[12:15], v[156:159]
	v_mfma_f32_16x16x32_bf16 v[156:159], v[144:147], v[8:11], v[124:127]
	v_mfma_f32_16x16x32_bf16 v[168:171], v[148:151], v[12:15], v[156:159]
	v_mfma_f32_16x16x32_bf16 v[156:159], v[152:155], v[8:11], v[124:127]
	v_mfma_f32_16x16x32_bf16 v[68:71], v[88:91], v[160:163], v[68:71]
	v_mfma_f32_16x16x32_bf16 v[64:67], v[96:99], v[160:163], v[64:67]
	v_mfma_f32_16x16x32_bf16 v[60:63], v[104:107], v[160:163], v[60:63]
	s_waitcnt lgkmcnt(0)
	v_mfma_f32_16x16x32_bf16 v[56:59], v[116:119], v[160:163], v[56:59]
	v_mfma_f32_16x16x32_bf16 v[160:163], v[140:143], v[12:15], v[156:159]
	s_and_saveexec_b64 s[8:9], s[6:7]
	s_xor_b64 s[8:9], exec, s[8:9]
	s_cbranch_execz .LBB0_553
	v_exp_f32_e32 v156, v184
	v_exp_f32_e32 v157, v185
	v_exp_f32_e32 v158, v186
	v_exp_f32_e32 v159, v187
	v_exp_f32_e32 v164, v176
	v_exp_f32_e32 v165, v177
	v_exp_f32_e32 v166, v178
	v_exp_f32_e32 v167, v179
	v_exp_f32_e32 v172, v168
	v_exp_f32_e32 v173, v169
	v_exp_f32_e32 v174, v170
	v_exp_f32_e32 v175, v171
	v_exp_f32_e32 v180, v160
	v_exp_f32_e32 v181, v161
	v_exp_f32_e32 v182, v162
	v_exp_f32_e32 v183, v163
	v_pk_add_f32 v[184:185], v[156:157], v[158:159]
	v_pk_add_f32 v[186:187], v[164:165], v[166:167]
	v_pk_add_f32 v[176:177], v[172:173], v[174:175]
	v_pk_add_f32 v[178:179], v[180:181], v[182:183]
	v_pk_add_f32 v[184:185], v[184:185], v[186:187]
	v_pk_add_f32 v[176:177], v[176:177], v[178:179]
	v_pk_add_f32 v[184:185], v[184:185], v[176:177]
	v_add_f32_e32 v243, v243, v184
	v_add_f32_e32 v243, v243, v185

; DI void nsa_item(const Params& p, int bk, int qb, char* smem, float Mb) {
;     ...
; #pragma unroll
;                 for (int g = 0; g < 3; ++g) {
;                     f32x4 st[4];
;                     st_from(kf, qf[g], st, -Ml);
;                     if (diag) {
; #pragma unroll
;                         for (int k4 = 0; k4 < 4; ++k4)
; #pragma unroll
;                             for (int ii = 0; ii < 4; ++ii) {
;                                 const float pv = (j * 64 + k4 * 16 + fq * 4 + ii <= tq) ? __builtin_amdgcn_exp2f(st[k4][ii]) : 0.f;
;                                 st[k4][ii] = pv; ls[g] += pv;
;                             }
;                     } else {
; #pragma unroll
;                         for (int k4 = 0; k4 < 4; ++k4)
; #pragma unroll
;                             for (int ii = 0; ii < 4; ++ii) { const float pv = __builtin_amdgcn_exp2f(st[k4][ii]); st[k4][ii] = pv; ls[g] += pv; }
;                     }
;                     pv_from(vf, st, o[g]);
;                 }
.LBB0_555:
	s_or_b64 exec, exec, s[14:15]
	v_cvt_pk_bf16_f32 v156, v156, v157
	v_cvt_pk_bf16_f32 v157, v158, v159
	v_cvt_pk_bf16_f32 v158, v164, v165
	v_cvt_pk_bf16_f32 v159, v166, v167
	v_mfma_f32_16x16x32_bf16 v[120:123], v[120:123], v[16:19], v[124:127]
	v_cvt_pk_bf16_f32 v160, v172, v173
	v_cvt_pk_bf16_f32 v161, v174, v175
	v_cvt_pk_bf16_f32 v162, v180, v181
	v_mfma_f32_16x16x32_bf16 v[52:55], v[108:111], v[156:159], v[52:55]
	v_cvt_pk_bf16_f32 v163, v182, v183
	v_mfma_f32_16x16x32_bf16 v[48:51], v[92:95], v[156:159], v[48:51]
	v_mfma_f32_16x16x32_bf16 v[44:47], v[100:103], v[156:159], v[44:47]
	v_mfma_f32_16x16x32_bf16 v[40:43], v[112:115], v[156:159], v[40:43]
	v_mfma_f32_16x16x32_bf16 v[52:55], v[88:91], v[160:163], v[52:55]
	v_mfma_f32_16x16x32_bf16 v[48:51], v[96:99], v[160:163], v[48:51]
	v_mfma_f32_16x16x32_bf16 v[44:47], v[104:107], v[160:163], v[44:47]
	v_mfma_f32_16x16x32_bf16 v[40:43], v[116:119], v[160:163], v[40:43]
	v_mfma_f32_16x16x32_bf16 v[160:163], v[128:131], v[20:23], v[120:123]
	v_mfma_f32_16x16x32_bf16 v[120:123], v[132:135], v[16:19], v[124:127]
	v_mfma_f32_16x16x32_bf16 v[156:159], v[136:139], v[20:23], v[120:123]
	v_mfma_f32_16x16x32_bf16 v[120:123], v[144:147], v[16:19], v[124:127]
	v_mfma_f32_16x16x32_bf16 v[124:127], v[152:155], v[16:19], v[124:127]
	v_mfma_f32_16x16x32_bf16 v[132:135], v[148:151], v[20:23], v[120:123]
	v_mfma_f32_16x16x32_bf16 v[124:127], v[140:143], v[20:23], v[124:127]
	s_and_saveexec_b64 s[8:9], s[6:7]
	s_xor_b64 s[6:7], exec, s[8:9]
	s_cbranch_execz .LBB0_557
	s_nop 1
	v_exp_f32_e32 v120, v160
	v_exp_f32_e32 v121, v161
	v_exp_f32_e32 v122, v162
	v_exp_f32_e32 v123, v163
	v_exp_f32_e32 v128, v156
	v_exp_f32_e32 v129, v157
	v_exp_f32_e32 v130, v158
	v_exp_f32_e32 v131, v159
	v_exp_f32_e32 v136, v132
	v_exp_f32_e32 v137, v133
	v_exp_f32_e32 v138, v134
	v_exp_f32_e32 v139, v135
	v_exp_f32_e32 v144, v124
	v_exp_f32_e32 v145, v125
	v_exp_f32_e32 v146, v126
	v_exp_f32_e32 v147, v127
	v_pk_add_f32 v[160:161], v[120:121], v[122:123]
	v_pk_add_f32 v[162:163], v[128:129], v[130:131]
	v_pk_add_f32 v[156:157], v[136:137], v[138:139]
	v_pk_add_f32 v[158:159], v[144:145], v[146:147]
	v_pk_add_f32 v[160:161], v[160:161], v[162:163]
	v_pk_add_f32 v[156:157], v[156:157], v[158:159]
	v_pk_add_f32 v[160:161], v[160:161], v[156:157]
	v_add_f32_e32 v241, v241, v160
	v_add_f32_e32 v241, v241, v161
